# L9 last layer final-norm output path: 4 gain quarters loaded up front with counted waits instead of load-wait-store one quarter at a time
# speedup vs baseline: 1.0050x; 1.0050x over previous
.LBB0_1336:
	v_readlane_b32 s14, v247, 37
	v_readlane_b32 s16, v247, 39
	s_andn2_b64 vcc, exec, s[2:3]
	v_readlane_b32 s15, v247, 38
	v_readlane_b32 s17, v247, 40
	s_cbranch_vccnz .LBB0_1325
	global_load_dwordx4 v[16:19], v[50:51], off
	global_load_dwordx4 v[22:25], v[50:51], off offset:16
	global_load_dwordx4 v[26:29], v[50:51], off offset:32
	global_load_dwordx4 v[30:33], v[50:51], off offset:48
	v_pk_mul_f32 v[8:9], v[8:9], v[66:67] op_sel_hi:[1,0]
	v_pk_mul_f32 v[10:11], v[10:11], v[66:67] op_sel_hi:[1,0]
	v_lshl_add_u64 v[20:21], v[62:63], 2, v[46:47]
	v_pk_mul_f32 v[12:13], v[12:13], v[66:67] op_sel_hi:[1,0]
	v_pk_mul_f32 v[14:15], v[14:15], v[66:67] op_sel_hi:[1,0]
	v_pk_mul_f32 v[4:5], v[4:5], v[66:67] op_sel_hi:[1,0]
	v_pk_mul_f32 v[6:7], v[6:7], v[66:67] op_sel_hi:[1,0]
	v_pk_mul_f32 v[0:1], v[0:1], v[66:67] op_sel_hi:[1,0]
	v_pk_mul_f32 v[2:3], v[2:3], v[66:67] op_sel_hi:[1,0]
	s_waitcnt vmcnt(3)
	v_pk_mul_f32 v[8:9], v[8:9], v[16:17]
	v_pk_mul_f32 v[10:11], v[10:11], v[18:19]
	global_store_dwordx4 v[20:21], v[8:11], off
	s_waitcnt vmcnt(3)
	v_pk_mul_f32 v[12:13], v[12:13], v[22:23]
	v_pk_mul_f32 v[14:15], v[14:15], v[24:25]
	global_store_dwordx4 v[20:21], v[12:15], off offset:16
	s_waitcnt vmcnt(3)
	v_pk_mul_f32 v[4:5], v[4:5], v[26:27]
	v_pk_mul_f32 v[6:7], v[6:7], v[28:29]
	global_store_dwordx4 v[20:21], v[4:7], off offset:32
	s_waitcnt vmcnt(3)
	v_pk_mul_f32 v[0:1], v[0:1], v[30:31]
	v_pk_mul_f32 v[2:3], v[2:3], v[32:33]
	global_store_dwordx4 v[20:21], v[0:3], off offset:48
	s_branch .LBB0_1325
